# combo+gblk+poolh + merge seam: alignment barrier moved after the first gate loads, last 4 gate loads hoisted above the second wait (vmcnt 4)
# baseline (speedup 1.0000x reference)
; __device__ __forceinline__ f32x4 un_unorm8(unsigned w) { return (f32x4){fmaxf((float)(w & 255u), 0.5f), fmaxf((float)((w >> 8) & 255u), 0.5f), fmaxf((float)((w >> 16) & 255u), 0.5f), fmaxf((float)(w >> 24), 0.5f)}; }
;     __device__ __forceinline__ void seam(f32x4 (&acc)[2][2][4][2], const Unit& u, int n, int wr, int wc, int fr, int fq) const {
;     ...
;         for (int ai = 0; ai < 2; ++ai) {
;             u32x2 ga[4][2], gb[4][2];
; #pragma unroll
;             for (int m = 0; m < 4; ++m)
; #pragma unroll
;                 for (int bj = 0; bj < 2; ++bj) { const int row = u.pm * 256 + ai * 128 + wr * 64 + m * 16 + fr, col = u.pn * 256 + bj * 128 + wc * 32 + 8 * fq;
;                     const unsigned char* gp = (const unsigned char*)P + (size_t)row * ROWB + GATE_B0 + n * DM + col; ga[m][bj] = *(const u32x2*)gp; gb[m][bj] = *(const u32x2*)(gp + DM); }
; #pragma unroll
;             for (int m = 0; m < 4; ++m)
; #pragma unroll
;                 for (int bj = 0; bj < 2; ++bj) { const f32x4 a0 = un_unorm8(ga[m][bj].x), a1 = un_unorm8(ga[m][bj].y), b0 = un_unorm8(gb[m][bj].x), b1 = un_unorm8(gb[m][bj].y);
; #pragma unroll
;                     for (int j = 0; j < 4; ++j) { acc[ai][bj][m][0][j] *= a0[j] * __builtin_amdgcn_rcpf(b0[j]); acc[ai][bj][m][1][j] *= a1[j] * __builtin_amdgcn_rcpf(b1[j]); } }
.LBB0_617:
	s_andn2_b64 vcc, exec, s[4:5]
	s_cbranch_vccnz .LBB0_619
	s_lshr_b32 s98, s42, 7
	s_bfe_u32 s99, s42, 0x10006
	s_or_b32 s98, s98, s99
	v_mov_b32_e32 v1, s98
	v_mov_b32_e32 v2, v181
	s_cmpk_eq_i32 s54, 0x800
	v_add_u32_e32 v1, s20, v1
	v_add_u32_e32 v154, s8, v1
	v_mov_b64_e32 v[148:149], s[68:69]
	s_cselect_b32 s56, 0, 0x800
	s_and_b32 s99, s42, 32
	s_lshl_b32 s99, s99, 4
	v_lshl_add_u32 v2, v2, 7, s99
	v_lshl_add_u32 v2, v180, 3, v2
	v_mad_i64_i32 v[150:151], s[4:5], v154, s33, v[148:149]
	v_ashrrev_i32_e32 v3, 31, v2
	v_lshl_add_u64 v[150:151], v[150:151], 0, s[56:57]
	v_lshl_add_u64 v[150:151], v[150:151], 0, v[2:3]
	v_lshl_add_u64 v[152:153], v[150:151], 0, s[64:65]
	v_add_co_u32_e32 v150, vcc, s12, v150
	global_load_dwordx2 v[184:185], v[152:153], off offset:2048
	s_nop 0
	v_addc_co_u32_e32 v151, vcc, 0, v151, vcc
	global_load_dwordx2 v[186:187], v[150:151], off
	global_load_dwordx2 v[208:209], v[152:153], off offset:3072
	global_load_dwordx2 v[210:211], v[152:153], off offset:1024
	v_add_u32_e32 v150, 16, v154
	v_add_u32_e32 v156, 48, v154
	v_mad_i64_i32 v[150:151], s[4:5], v150, s33, v[148:149]
	v_mad_i64_i32 v[156:157], s[4:5], v156, s33, v[148:149]
	v_lshl_add_u64 v[150:151], v[150:151], 0, s[56:57]
	v_lshl_add_u64 v[156:157], v[156:157], 0, s[56:57]
	v_lshl_add_u64 v[150:151], v[150:151], 0, v[2:3]
	v_lshl_add_u64 v[152:153], v[156:157], 0, v[2:3]
	v_lshl_add_u64 v[156:157], v[150:151], 0, s[64:65]
	v_add_co_u32_e32 v150, vcc, s12, v150
	v_add_u32_e32 v155, 32, v154
	s_nop 0
	v_addc_co_u32_e32 v151, vcc, 0, v151, vcc
	global_load_dwordx2 v[176:177], v[156:157], off offset:2048
	global_load_dwordx2 v[178:179], v[150:151], off
	global_load_dwordx2 v[172:173], v[156:157], off offset:3072
	global_load_dwordx2 v[174:175], v[156:157], off offset:1024
	v_mad_i64_i32 v[154:155], s[4:5], v155, s33, v[148:149]
	v_lshl_add_u64 v[154:155], v[154:155], 0, s[56:57]
	v_lshl_add_u64 v[154:155], v[154:155], 0, v[2:3]
	v_lshl_add_u64 v[160:161], v[154:155], 0, s[64:65]
	v_add_co_u32_e32 v154, vcc, s12, v154
	v_lshl_add_u64 v[212:213], v[152:153], 0, s[64:65]
	s_nop 0
	v_addc_co_u32_e32 v155, vcc, 0, v155, vcc
	global_load_dwordx2 v[168:169], v[160:161], off offset:2048
	global_load_dwordx2 v[170:171], v[154:155], off
	global_load_dwordx2 v[158:159], v[160:161], off offset:3072
	s_nop 0
	global_load_dwordx2 v[160:161], v[160:161], off offset:1024
	v_add_co_u32_e32 v150, vcc, s12, v152
	v_add_u32_e32 v1, s43, v1
	s_nop 0
	v_addc_co_u32_e32 v151, vcc, 0, v153, vcc
	global_load_dwordx2 v[154:155], v[212:213], off offset:2048
	global_load_dwordx2 v[156:157], v[150:151], off
	s_nop 0
	global_load_dwordx2 v[150:151], v[212:213], off offset:3072
	global_load_dwordx2 v[152:153], v[212:213], off offset:1024
	s_and_b64 vcc, exec, s[46:47]
	s_cbranch_vccz .Lsm_a
	s_barrier
.Lsm_a:
	s_waitcnt vmcnt(0)
	v_cvt_f32_ubyte0_e32 v212, v184
	v_cvt_f32_ubyte1_e32 v213, v184
	v_cvt_f32_ubyte2_e32 v214, v184
	v_cvt_f32_ubyte0_e32 v219, v187
	v_cvt_f32_ubyte3_e32 v184, v184
	v_cvt_f32_ubyte3_e32 v218, v186
	v_max_f32_e32 v225, 0.5, v214
	v_max_f32_e32 v214, 0.5, v219
	v_max_f32_e32 v219, 0.5, v184
	v_cvt_f32_ubyte0_e32 v184, v185
	v_cvt_f32_ubyte2_e32 v217, v186
	v_cvt_f32_ubyte3_e32 v222, v187
	v_max_f32_e32 v224, 0.5, v213
	v_max_f32_e32 v213, 0.5, v218
	v_max_f32_e32 v218, 0.5, v184
	v_cvt_f32_ubyte1_e32 v184, v185
	v_max_f32_e32 v223, 0.5, v212
	v_max_f32_e32 v212, 0.5, v217
	v_max_f32_e32 v217, 0.5, v222
	v_max_f32_e32 v222, 0.5, v184
	v_cvt_f32_ubyte2_e32 v184, v185
	v_cvt_f32_ubyte0_e32 v215, v186
	v_cvt_f32_ubyte1_e32 v216, v186
	v_cvt_f32_ubyte1_e32 v220, v187
	v_cvt_f32_ubyte2_e32 v221, v187
	v_max_f32_e32 v226, 0.5, v184
	v_cvt_f32_ubyte3_e32 v184, v185
	v_max_f32_e32 v186, 0.5, v215
	v_max_f32_e32 v187, 0.5, v216
	v_max_f32_e32 v215, 0.5, v220
	v_max_f32_e32 v216, 0.5, v221
	v_max_f32_e32 v227, 0.5, v184
	v_rcp_f32_e32 v184, v223
	v_rcp_f32_e32 v185, v224
	v_rcp_f32_e32 v220, v225
	v_rcp_f32_e32 v221, v219
	v_rcp_f32_e32 v218, v218
	v_rcp_f32_e32 v219, v222
	v_rcp_f32_e32 v222, v226
	v_rcp_f32_e32 v223, v227
	v_pk_mul_f32 v[184:185], v[186:187], v[184:185]
	v_pk_mul_f32 v[186:187], v[212:213], v[220:221]
	v_pk_mul_f32 v[128:129], v[128:129], v[184:185]
	v_pk_mul_f32 v[130:131], v[130:131], v[186:187]
	v_pk_mul_f32 v[184:185], v[214:215], v[218:219]
	v_pk_mul_f32 v[186:187], v[216:217], v[222:223]
	v_cvt_f32_ubyte0_e32 v214, v208
	v_cvt_f32_ubyte1_e32 v215, v208
	v_cvt_f32_ubyte2_e32 v216, v208
	v_cvt_f32_ubyte3_e32 v208, v208
	v_max_f32_e32 v217, 0.5, v208
	v_cvt_f32_ubyte0_e32 v208, v209
	v_max_f32_e32 v218, 0.5, v208
	v_cvt_f32_ubyte1_e32 v208, v209
	v_max_f32_e32 v219, 0.5, v208
	v_cvt_f32_ubyte2_e32 v208, v209
	v_max_f32_e32 v214, 0.5, v214
	v_max_f32_e32 v215, 0.5, v215
	v_max_f32_e32 v216, 0.5, v216
	v_max_f32_e32 v220, 0.5, v208
	v_cvt_f32_ubyte3_e32 v208, v209
	v_max_f32_e32 v221, 0.5, v208
	v_rcp_f32_e32 v208, v214
	v_rcp_f32_e32 v209, v215
	v_rcp_f32_e32 v216, v216
	v_rcp_f32_e32 v217, v217
	v_pk_mul_f32 v[126:127], v[126:127], v[186:187]
	v_pk_mul_f32 v[124:125], v[124:125], v[184:185]
	v_cvt_f32_ubyte0_e32 v184, v210
	v_cvt_f32_ubyte1_e32 v185, v210
	v_cvt_f32_ubyte2_e32 v186, v210
	v_cvt_f32_ubyte3_e32 v187, v210
	v_cvt_f32_ubyte0_e32 v210, v211
	v_rcp_f32_e32 v214, v218
	v_rcp_f32_e32 v215, v219
	v_rcp_f32_e32 v218, v220
	v_rcp_f32_e32 v219, v221
	v_max_f32_e32 v212, 0.5, v210
	v_cvt_f32_ubyte1_e32 v210, v211
	v_max_f32_e32 v184, 0.5, v184
	v_max_f32_e32 v185, 0.5, v185
	v_max_f32_e32 v186, 0.5, v186
	v_max_f32_e32 v187, 0.5, v187
	v_max_f32_e32 v213, 0.5, v210
	v_cvt_f32_ubyte2_e32 v210, v211
	v_cvt_f32_ubyte3_e32 v211, v211
; __device__ __forceinline__ f32x4 un_unorm8(unsigned w) { return (f32x4){fmaxf((float)(w & 255u), 0.5f), fmaxf((float)((w >> 8) & 255u), 0.5f), fmaxf((float)((w >> 16) & 255u), 0.5f), fmaxf((float)(w >> 24), 0.5f)}; }
;     __device__ __forceinline__ void seam(f32x4 (&acc)[2][2][4][2], const Unit& u, int n, int wr, int wc, int fr, int fq) const {
;     ...
;             for (int m = 0; m < 4; ++m)
; #pragma unroll
;                 for (int bj = 0; bj < 2; ++bj) { const f32x4 a0 = un_unorm8(ga[m][bj].x), a1 = un_unorm8(ga[m][bj].y), b0 = un_unorm8(gb[m][bj].x), b1 = un_unorm8(gb[m][bj].y);
; #pragma unroll
;                     for (int j = 0; j < 4; ++j) { acc[ai][bj][m][0][j] *= a0[j] * __builtin_amdgcn_rcpf(b0[j]); acc[ai][bj][m][1][j] *= a1[j] * __builtin_amdgcn_rcpf(b1[j]); } }
	v_max_f32_e32 v210, 0.5, v210
	v_max_f32_e32 v211, 0.5, v211
	v_pk_mul_f32 v[184:185], v[184:185], v[208:209]
	v_pk_mul_f32 v[186:187], v[186:187], v[216:217]
	v_pk_mul_f32 v[120:121], v[120:121], v[184:185]
	v_pk_mul_f32 v[122:123], v[122:123], v[186:187]
	v_pk_mul_f32 v[184:185], v[212:213], v[214:215]
	v_pk_mul_f32 v[186:187], v[210:211], v[218:219]
	v_cvt_f32_ubyte0_e32 v210, v176
	v_cvt_f32_ubyte1_e32 v211, v176
	v_cvt_f32_ubyte2_e32 v212, v176
	v_cvt_f32_ubyte3_e32 v176, v176
	v_max_f32_e32 v213, 0.5, v176
	v_cvt_f32_ubyte0_e32 v176, v177
	v_max_f32_e32 v214, 0.5, v176
	v_cvt_f32_ubyte1_e32 v176, v177
	v_max_f32_e32 v215, 0.5, v176
	v_cvt_f32_ubyte2_e32 v176, v177
	v_max_f32_e32 v210, 0.5, v210
	v_max_f32_e32 v211, 0.5, v211
	v_max_f32_e32 v216, 0.5, v176
	v_cvt_f32_ubyte3_e32 v176, v177
	v_max_f32_e32 v212, 0.5, v212
	v_max_f32_e32 v217, 0.5, v176
	v_rcp_f32_e32 v176, v210
	v_rcp_f32_e32 v177, v211
	v_pk_mul_f32 v[118:119], v[118:119], v[186:187]
	v_pk_mul_f32 v[116:117], v[116:117], v[184:185]
	v_cvt_f32_ubyte0_e32 v184, v178
	v_cvt_f32_ubyte1_e32 v185, v178
	v_cvt_f32_ubyte2_e32 v186, v178
	v_cvt_f32_ubyte3_e32 v178, v178
	v_rcp_f32_e32 v210, v214
	v_rcp_f32_e32 v212, v212
	v_rcp_f32_e32 v213, v213
	v_rcp_f32_e32 v211, v215
	v_max_f32_e32 v187, 0.5, v178
	v_cvt_f32_ubyte0_e32 v178, v179
	v_max_f32_e32 v184, 0.5, v184
	v_max_f32_e32 v185, 0.5, v185
	v_max_f32_e32 v208, 0.5, v178
	v_cvt_f32_ubyte1_e32 v178, v179
	v_max_f32_e32 v186, 0.5, v186
	v_max_f32_e32 v209, 0.5, v178
	v_pk_mul_f32 v[176:177], v[184:185], v[176:177]
	v_pk_mul_f32 v[184:185], v[186:187], v[212:213]
	v_pk_mul_f32 v[112:113], v[112:113], v[176:177]
	v_pk_mul_f32 v[176:177], v[208:209], v[210:211]
	v_cvt_f32_ubyte0_e32 v186, v172
	v_cvt_f32_ubyte1_e32 v187, v172
	v_cvt_f32_ubyte2_e32 v208, v172
	v_cvt_f32_ubyte3_e32 v172, v172
	v_rcp_f32_e32 v214, v216
	v_rcp_f32_e32 v215, v217
	v_max_f32_e32 v209, 0.5, v172
	v_cvt_f32_ubyte0_e32 v172, v173
	v_max_f32_e32 v210, 0.5, v172
	v_cvt_f32_ubyte1_e32 v172, v173
	v_cvt_f32_ubyte2_e32 v178, v179
	v_cvt_f32_ubyte3_e32 v179, v179
	v_max_f32_e32 v211, 0.5, v172
	v_cvt_f32_ubyte2_e32 v172, v173
	v_max_f32_e32 v178, 0.5, v178
	v_max_f32_e32 v179, 0.5, v179
	v_max_f32_e32 v186, 0.5, v186
	v_max_f32_e32 v187, 0.5, v187
	v_max_f32_e32 v212, 0.5, v172
	v_cvt_f32_ubyte3_e32 v172, v173
	v_pk_mul_f32 v[178:179], v[178:179], v[214:215]
	v_max_f32_e32 v208, 0.5, v208
	v_max_f32_e32 v213, 0.5, v172
	v_rcp_f32_e32 v172, v186
	v_rcp_f32_e32 v173, v187
	v_pk_mul_f32 v[110:111], v[110:111], v[178:179]
	v_pk_mul_f32 v[108:109], v[108:109], v[176:177]
	v_cvt_f32_ubyte0_e32 v176, v174
	v_cvt_f32_ubyte1_e32 v177, v174
	v_cvt_f32_ubyte2_e32 v178, v174
	v_cvt_f32_ubyte3_e32 v174, v174
	v_rcp_f32_e32 v186, v210
	v_rcp_f32_e32 v208, v208
	v_rcp_f32_e32 v209, v209
	v_rcp_f32_e32 v187, v211
	v_max_f32_e32 v179, 0.5, v174
	v_cvt_f32_ubyte0_e32 v174, v175
	v_pk_mul_f32 v[114:115], v[114:115], v[184:185]
	v_max_f32_e32 v176, 0.5, v176
	v_max_f32_e32 v177, 0.5, v177
	v_max_f32_e32 v184, 0.5, v174
	v_cvt_f32_ubyte1_e32 v174, v175
	v_max_f32_e32 v178, 0.5, v178
	v_max_f32_e32 v185, 0.5, v174
	v_pk_mul_f32 v[172:173], v[176:177], v[172:173]
	v_pk_mul_f32 v[176:177], v[178:179], v[208:209]
	v_pk_mul_f32 v[104:105], v[104:105], v[172:173]
	v_pk_mul_f32 v[172:173], v[184:185], v[186:187]
	v_cvt_f32_ubyte0_e32 v178, v168
	v_cvt_f32_ubyte1_e32 v179, v168
	v_cvt_f32_ubyte2_e32 v184, v168
	v_cvt_f32_ubyte3_e32 v168, v168
	v_rcp_f32_e32 v210, v212
	v_rcp_f32_e32 v211, v213
	v_max_f32_e32 v185, 0.5, v168
	v_cvt_f32_ubyte0_e32 v168, v169
	v_max_f32_e32 v186, 0.5, v168
	v_cvt_f32_ubyte1_e32 v168, v169
	v_cvt_f32_ubyte2_e32 v174, v175
	v_cvt_f32_ubyte3_e32 v175, v175
	v_max_f32_e32 v187, 0.5, v168
	v_cvt_f32_ubyte2_e32 v168, v169
	v_max_f32_e32 v174, 0.5, v174
	v_max_f32_e32 v175, 0.5, v175
	v_max_f32_e32 v178, 0.5, v178
	v_max_f32_e32 v179, 0.5, v179
	v_max_f32_e32 v208, 0.5, v168
	v_cvt_f32_ubyte3_e32 v168, v169
	v_pk_mul_f32 v[174:175], v[174:175], v[210:211]
	v_max_f32_e32 v184, 0.5, v184
	v_max_f32_e32 v209, 0.5, v168
	v_rcp_f32_e32 v168, v178
	v_rcp_f32_e32 v169, v179
	v_pk_mul_f32 v[102:103], v[102:103], v[174:175]
	v_pk_mul_f32 v[100:101], v[100:101], v[172:173]
	v_cvt_f32_ubyte0_e32 v172, v170
	v_cvt_f32_ubyte1_e32 v173, v170
	v_cvt_f32_ubyte2_e32 v174, v170
	v_cvt_f32_ubyte3_e32 v170, v170
	v_rcp_f32_e32 v178, v186
	v_rcp_f32_e32 v184, v184
	v_rcp_f32_e32 v185, v185
	v_rcp_f32_e32 v179, v187
	v_max_f32_e32 v175, 0.5, v170
	v_cvt_f32_ubyte0_e32 v170, v171
	v_pk_mul_f32 v[106:107], v[106:107], v[176:177]
	v_max_f32_e32 v172, 0.5, v172
	v_max_f32_e32 v173, 0.5, v173
	v_max_f32_e32 v176, 0.5, v170
	v_cvt_f32_ubyte1_e32 v170, v171
	v_max_f32_e32 v174, 0.5, v174
	v_max_f32_e32 v177, 0.5, v170
	v_pk_mul_f32 v[168:169], v[172:173], v[168:169]
	v_pk_mul_f32 v[172:173], v[174:175], v[184:185]
	v_pk_mul_f32 v[96:97], v[96:97], v[168:169]
	v_pk_mul_f32 v[168:169], v[176:177], v[178:179]
	v_cvt_f32_ubyte0_e32 v174, v158
	v_cvt_f32_ubyte1_e32 v175, v158
	v_cvt_f32_ubyte2_e32 v176, v158
	v_cvt_f32_ubyte3_e32 v158, v158
	v_rcp_f32_e32 v186, v208
	v_rcp_f32_e32 v187, v209
	v_max_f32_e32 v177, 0.5, v158
	v_cvt_f32_ubyte0_e32 v158, v159
	v_max_f32_e32 v178, 0.5, v158
	v_cvt_f32_ubyte1_e32 v158, v159
	v_cvt_f32_ubyte2_e32 v170, v171
	v_cvt_f32_ubyte3_e32 v171, v171
	v_max_f32_e32 v179, 0.5, v158
	v_cvt_f32_ubyte2_e32 v158, v159
	v_max_f32_e32 v170, 0.5, v170
	v_max_f32_e32 v171, 0.5, v171
	v_max_f32_e32 v174, 0.5, v174
	v_max_f32_e32 v175, 0.5, v175
	v_max_f32_e32 v184, 0.5, v158
	v_cvt_f32_ubyte3_e32 v158, v159
	v_pk_mul_f32 v[170:171], v[170:171], v[186:187]
; __device__ __forceinline__ f32x4 un_unorm8(unsigned w) { return (f32x4){fmaxf((float)(w & 255u), 0.5f), fmaxf((float)((w >> 8) & 255u), 0.5f), fmaxf((float)((w >> 16) & 255u), 0.5f), fmaxf((float)(w >> 24), 0.5f)}; }
;     __device__ __forceinline__ void seam(f32x4 (&acc)[2][2][4][2], const Unit& u, int n, int wr, int wc, int fr, int fq) const {
;     ...
;         for (int ai = 0; ai < 2; ++ai) {
;             u32x2 ga[4][2], gb[4][2];
; #pragma unroll
;             for (int m = 0; m < 4; ++m)
; #pragma unroll
;                 for (int bj = 0; bj < 2; ++bj) { const int row = u.pm * 256 + ai * 128 + wr * 64 + m * 16 + fr, col = u.pn * 256 + bj * 128 + wc * 32 + 8 * fq;
;                     const unsigned char* gp = (const unsigned char*)P + (size_t)row * ROWB + GATE_B0 + n * DM + col; ga[m][bj] = *(const u32x2*)gp; gb[m][bj] = *(const u32x2*)(gp + DM); }
; #pragma unroll
;             for (int m = 0; m < 4; ++m)
; #pragma unroll
;                 for (int bj = 0; bj < 2; ++bj) { const f32x4 a0 = un_unorm8(ga[m][bj].x), a1 = un_unorm8(ga[m][bj].y), b0 = un_unorm8(gb[m][bj].x), b1 = un_unorm8(gb[m][bj].y);
; #pragma unroll
;                     for (int j = 0; j < 4; ++j) { acc[ai][bj][m][0][j] *= a0[j] * __builtin_amdgcn_rcpf(b0[j]); acc[ai][bj][m][1][j] *= a1[j] * __builtin_amdgcn_rcpf(b1[j]); } }
	v_max_f32_e32 v176, 0.5, v176
	v_max_f32_e32 v185, 0.5, v158
	v_rcp_f32_e32 v158, v174
	v_rcp_f32_e32 v159, v175
	v_pk_mul_f32 v[94:95], v[94:95], v[170:171]
	v_pk_mul_f32 v[92:93], v[92:93], v[168:169]
	v_cvt_f32_ubyte0_e32 v168, v160
	v_cvt_f32_ubyte1_e32 v169, v160
	v_cvt_f32_ubyte2_e32 v170, v160
	v_cvt_f32_ubyte3_e32 v160, v160
	v_rcp_f32_e32 v174, v178
	v_rcp_f32_e32 v176, v176
	v_rcp_f32_e32 v177, v177
	v_rcp_f32_e32 v175, v179
	v_max_f32_e32 v171, 0.5, v160
	v_cvt_f32_ubyte0_e32 v160, v161
	v_pk_mul_f32 v[98:99], v[98:99], v[172:173]
	v_max_f32_e32 v168, 0.5, v168
	v_max_f32_e32 v169, 0.5, v169
	v_max_f32_e32 v172, 0.5, v160
	v_cvt_f32_ubyte1_e32 v160, v161
	v_max_f32_e32 v170, 0.5, v170
	v_max_f32_e32 v173, 0.5, v160
	v_pk_mul_f32 v[158:159], v[168:169], v[158:159]
	v_pk_mul_f32 v[168:169], v[170:171], v[176:177]
	v_pk_mul_f32 v[88:89], v[88:89], v[158:159]
	v_pk_mul_f32 v[158:159], v[172:173], v[174:175]
	v_cvt_f32_ubyte0_e32 v170, v154
	v_cvt_f32_ubyte1_e32 v171, v154
	v_cvt_f32_ubyte2_e32 v172, v154
	v_cvt_f32_ubyte3_e32 v154, v154
	v_max_f32_e32 v173, 0.5, v154
	v_cvt_f32_ubyte0_e32 v154, v155
	v_rcp_f32_e32 v178, v184
	v_rcp_f32_e32 v179, v185
	v_max_f32_e32 v174, 0.5, v154
	v_cvt_f32_ubyte1_e32 v154, v155
	v_max_f32_e32 v175, 0.5, v154
	v_cvt_f32_ubyte2_e32 v154, v155
	v_cvt_f32_ubyte2_e32 v160, v161
	v_cvt_f32_ubyte3_e32 v161, v161
	v_max_f32_e32 v170, 0.5, v170
	v_max_f32_e32 v171, 0.5, v171
	v_max_f32_e32 v172, 0.5, v172
	v_max_f32_e32 v176, 0.5, v154
	v_cvt_f32_ubyte3_e32 v154, v155
	v_max_f32_e32 v160, 0.5, v160
	v_max_f32_e32 v161, 0.5, v161
	v_max_f32_e32 v177, 0.5, v154
	v_rcp_f32_e32 v154, v170
	v_rcp_f32_e32 v155, v171
	v_rcp_f32_e32 v172, v172
	v_rcp_f32_e32 v173, v173
	v_pk_mul_f32 v[160:161], v[160:161], v[178:179]
	v_pk_mul_f32 v[84:85], v[84:85], v[158:159]
	v_pk_mul_f32 v[86:87], v[86:87], v[160:161]
	v_cvt_f32_ubyte0_e32 v158, v156
	v_cvt_f32_ubyte1_e32 v159, v156
	v_cvt_f32_ubyte2_e32 v160, v156
	v_cvt_f32_ubyte3_e32 v156, v156
	v_max_f32_e32 v158, 0.5, v158
	v_max_f32_e32 v159, 0.5, v159
	v_max_f32_e32 v160, 0.5, v160
	v_max_f32_e32 v161, 0.5, v156
	v_rcp_f32_e32 v170, v174
	v_rcp_f32_e32 v171, v175
	v_cvt_f32_ubyte0_e32 v156, v157
	v_pk_mul_f32 v[154:155], v[158:159], v[154:155]
	v_pk_mul_f32 v[158:159], v[160:161], v[172:173]
	v_mad_i64_i32 v[160:161], s[4:5], v1, s33, v[148:149]
	v_pk_mul_f32 v[90:91], v[90:91], v[168:169]
	v_max_f32_e32 v168, 0.5, v156
	v_cvt_f32_ubyte1_e32 v156, v157
	v_lshl_add_u64 v[160:161], v[160:161], 0, s[56:57]
	v_max_f32_e32 v169, 0.5, v156
	v_lshl_add_u64 v[160:161], v[160:161], 0, v[2:3]
	v_pk_mul_f32 v[80:81], v[80:81], v[154:155]
	v_pk_mul_f32 v[154:155], v[168:169], v[170:171]
	v_add_co_u32_e32 v168, vcc, s12, v160
	v_rcp_f32_e32 v174, v176
	s_nop 0
	v_addc_co_u32_e32 v169, vcc, 0, v161, vcc
	global_load_dwordx2 v[172:173], v[168:169], off
	v_rcp_f32_e32 v175, v177
	v_cvt_f32_ubyte2_e32 v156, v157
	v_cvt_f32_ubyte3_e32 v157, v157
	v_max_f32_e32 v156, 0.5, v156
	v_max_f32_e32 v157, 0.5, v157
	v_lshl_add_u64 v[160:161], v[160:161], 0, s[64:65]
	v_pk_mul_f32 v[156:157], v[156:157], v[174:175]
	global_load_dwordx2 v[174:175], v[160:161], off offset:2048
	v_cvt_f32_ubyte0_e32 v168, v150
	v_cvt_f32_ubyte1_e32 v169, v150
	v_cvt_f32_ubyte2_e32 v170, v150
	v_cvt_f32_ubyte3_e32 v150, v150
	v_max_f32_e32 v171, 0.5, v150
	v_cvt_f32_ubyte0_e32 v150, v151
	v_max_f32_e32 v176, 0.5, v150
	v_cvt_f32_ubyte1_e32 v150, v151
	v_max_f32_e32 v177, 0.5, v150
	v_cvt_f32_ubyte2_e32 v150, v151
	v_max_f32_e32 v178, 0.5, v150
	v_cvt_f32_ubyte3_e32 v150, v151
	v_pk_mul_f32 v[78:79], v[78:79], v[156:157]
	v_pk_mul_f32 v[76:77], v[76:77], v[154:155]
	v_cvt_f32_ubyte0_e32 v154, v152
	v_cvt_f32_ubyte1_e32 v155, v152
	v_cvt_f32_ubyte2_e32 v156, v152
	v_cvt_f32_ubyte3_e32 v152, v152
	v_max_f32_e32 v168, 0.5, v168
	v_max_f32_e32 v169, 0.5, v169
	v_max_f32_e32 v179, 0.5, v150
	v_max_f32_e32 v157, 0.5, v152
	v_cvt_f32_ubyte0_e32 v152, v153
	v_rcp_f32_e32 v150, v168
	v_rcp_f32_e32 v168, v176
	v_rcp_f32_e32 v151, v169
	v_rcp_f32_e32 v169, v177
	v_rcp_f32_e32 v176, v178
	v_rcp_f32_e32 v177, v179
	v_pk_mul_f32 v[82:83], v[82:83], v[158:159]
	v_max_f32_e32 v158, 0.5, v152
	v_cvt_f32_ubyte1_e32 v152, v153
	v_max_f32_e32 v159, 0.5, v152
	v_cvt_f32_ubyte2_e32 v152, v153
	v_cvt_f32_ubyte3_e32 v153, v153
	v_max_f32_e32 v152, 0.5, v152
	v_max_f32_e32 v153, 0.5, v153
	v_pk_mul_f32 v[152:153], v[152:153], v[176:177]
	global_load_dwordx2 v[176:177], v[160:161], off offset:3072
	global_load_dwordx2 v[178:179], v[160:161], off offset:1024
	v_max_f32_e32 v154, 0.5, v154
	v_max_f32_e32 v155, 0.5, v155
	v_pk_mul_f32 v[150:151], v[154:155], v[150:151]
	v_max_f32_e32 v170, 0.5, v170
	v_pk_mul_f32 v[72:73], v[72:73], v[150:151]
	v_pk_mul_f32 v[150:151], v[158:159], v[168:169]
	v_rcp_f32_e32 v170, v170
	v_pk_mul_f32 v[68:69], v[68:69], v[150:151]
	v_add_u32_e32 v150, 16, v1
	v_mad_i64_i32 v[150:151], s[4:5], v150, s33, v[148:149]
	v_rcp_f32_e32 v171, v171
	v_lshl_add_u64 v[150:151], v[150:151], 0, s[56:57]
	v_lshl_add_u64 v[150:151], v[150:151], 0, v[2:3]
	v_pk_mul_f32 v[70:71], v[70:71], v[152:153]
	v_lshl_add_u64 v[152:153], v[150:151], 0, s[64:65]
	v_add_co_u32_e32 v150, vcc, s12, v150
	v_max_f32_e32 v156, 0.5, v156
	s_nop 0
	v_addc_co_u32_e32 v151, vcc, 0, v151, vcc
	v_pk_mul_f32 v[154:155], v[156:157], v[170:171]
	global_load_dwordx2 v[184:185], v[150:151], off
	global_load_dwordx2 v[186:187], v[152:153], off offset:2048
	global_load_dwordx2 v[168:169], v[152:153], off offset:3072
	global_load_dwordx2 v[170:171], v[152:153], off offset:1024
	v_add_u32_e32 v150, 32, v1
	v_mad_i64_i32 v[150:151], s[4:5], v150, s33, v[148:149]
	v_lshl_add_u64 v[150:151], v[150:151], 0, s[56:57]
	v_lshl_add_u64 v[150:151], v[150:151], 0, v[2:3]
	v_lshl_add_u64 v[152:153], v[150:151], 0, s[64:65]
	v_add_co_u32_e32 v150, vcc, s12, v150
	v_pk_mul_f32 v[74:75], v[74:75], v[154:155]
	s_nop 0
	v_addc_co_u32_e32 v151, vcc, 0, v151, vcc
	global_load_dwordx2 v[160:161], v[150:151], off
	global_load_dwordx2 v[158:159], v[152:153], off offset:2048
	global_load_dwordx2 v[154:155], v[152:153], off offset:3072
	global_load_dwordx2 v[156:157], v[152:153], off offset:1024
	v_add_u32_e32 v1, 48, v1
	v_mad_i64_i32 v[148:149], s[4:5], v1, s33, v[148:149]
	v_lshl_add_u64 v[148:149], v[148:149], 0, s[56:57]
	v_lshl_add_u64 v[2:3], v[148:149], 0, v[2:3]
	v_lshl_add_u64 v[148:149], v[2:3], 0, s[64:65]
	v_add_co_u32_e32 v2, vcc, s12, v2
	v_addc_co_u32_e32 v3, vcc, 0, v3, vcc
	global_load_dwordx2 v[152:153], v[2:3], off
	global_load_dwordx2 v[150:151], v[148:149], off offset:2048
	s_nop 0
	global_load_dwordx2 v[2:3], v[148:149], off offset:3072
	s_nop 0
	global_load_dwordx2 v[148:149], v[148:149], off offset:1024
	s_waitcnt vmcnt(4)
; __device__ __forceinline__ f32x4 un_unorm8(unsigned w) { return (f32x4){fmaxf((float)(w & 255u), 0.5f), fmaxf((float)((w >> 8) & 255u), 0.5f), fmaxf((float)((w >> 16) & 255u), 0.5f), fmaxf((float)(w >> 24), 0.5f)}; }
;     __device__ __forceinline__ void seam(f32x4 (&acc)[2][2][4][2], const Unit& u, int n, int wr, int wc, int fr, int fq) const {
;     ...
;             for (int m = 0; m < 4; ++m)
; #pragma unroll
;                 for (int bj = 0; bj < 2; ++bj) { const f32x4 a0 = un_unorm8(ga[m][bj].x), a1 = un_unorm8(ga[m][bj].y), b0 = un_unorm8(gb[m][bj].x), b1 = un_unorm8(gb[m][bj].y);
; #pragma unroll
;                     for (int j = 0; j < 4; ++j) { acc[ai][bj][m][0][j] *= a0[j] * __builtin_amdgcn_rcpf(b0[j]); acc[ai][bj][m][1][j] *= a1[j] * __builtin_amdgcn_rcpf(b1[j]); } }
	v_cvt_f32_ubyte0_e32 v1, v172
	v_max_f32_e32 v208, 0.5, v1
	v_cvt_f32_ubyte1_e32 v1, v172
	v_max_f32_e32 v209, 0.5, v1
	v_cvt_f32_ubyte2_e32 v1, v172
	v_max_f32_e32 v210, 0.5, v1
	v_cvt_f32_ubyte3_e32 v1, v172
	v_max_f32_e32 v211, 0.5, v1
	v_cvt_f32_ubyte0_e32 v1, v173
	v_max_f32_e32 v212, 0.5, v1
	v_cvt_f32_ubyte1_e32 v1, v173
	v_max_f32_e32 v213, 0.5, v1
	v_cvt_f32_ubyte2_e32 v1, v173
	v_max_f32_e32 v172, 0.5, v1
	v_cvt_f32_ubyte3_e32 v1, v173
	v_cvt_f32_ubyte1_e32 v214, v174
	v_max_f32_e32 v173, 0.5, v1
	v_cvt_f32_ubyte0_e32 v1, v174
	v_max_f32_e32 v215, 0.5, v214
	v_cvt_f32_ubyte2_e32 v214, v174
	v_cvt_f32_ubyte3_e32 v174, v174
	v_max_f32_e32 v217, 0.5, v174
	v_cvt_f32_ubyte0_e32 v174, v175
	v_max_f32_e32 v216, 0.5, v214
	v_max_f32_e32 v214, 0.5, v174
	v_cvt_f32_ubyte1_e32 v174, v175
	v_max_f32_e32 v218, 0.5, v174
	v_cvt_f32_ubyte2_e32 v174, v175
	v_max_f32_e32 v219, 0.5, v174
	v_cvt_f32_ubyte3_e32 v174, v175
	v_max_f32_e32 v220, 0.5, v174
	v_max_f32_e32 v1, 0.5, v1
	v_rcp_f32_e32 v175, v215
	v_rcp_f32_e32 v215, v218
	v_rcp_f32_e32 v218, v219
	v_rcp_f32_e32 v219, v220
	v_rcp_f32_e32 v174, v1
	v_rcp_f32_e32 v214, v214
	v_rcp_f32_e32 v216, v216
	v_rcp_f32_e32 v217, v217
	v_pk_mul_f32 v[172:173], v[172:173], v[218:219]
	v_cvt_f32_ubyte0_e32 v1, v178
	v_pk_mul_f32 v[174:175], v[208:209], v[174:175]
	v_pk_mul_f32 v[62:63], v[62:63], v[172:173]
	v_max_f32_e32 v172, 0.5, v1
	v_cvt_f32_ubyte1_e32 v1, v178
	v_pk_mul_f32 v[64:65], v[64:65], v[174:175]
	v_pk_mul_f32 v[174:175], v[212:213], v[214:215]
	v_max_f32_e32 v173, 0.5, v1
	v_cvt_f32_ubyte2_e32 v1, v178
	v_pk_mul_f32 v[60:61], v[60:61], v[174:175]
	v_max_f32_e32 v174, 0.5, v1
	v_cvt_f32_ubyte3_e32 v1, v178
	v_pk_mul_f32 v[208:209], v[210:211], v[216:217]
	v_max_f32_e32 v175, 0.5, v1
	v_cvt_f32_ubyte0_e32 v1, v179
	v_pk_mul_f32 v[66:67], v[66:67], v[208:209]
	v_max_f32_e32 v208, 0.5, v1
	v_cvt_f32_ubyte1_e32 v1, v179
	v_max_f32_e32 v209, 0.5, v1
	v_cvt_f32_ubyte2_e32 v1, v179
	v_max_f32_e32 v178, 0.5, v1
	v_cvt_f32_ubyte3_e32 v1, v179
	v_cvt_f32_ubyte1_e32 v210, v176
	v_max_f32_e32 v179, 0.5, v1
	v_cvt_f32_ubyte0_e32 v1, v176
	v_max_f32_e32 v211, 0.5, v210
	v_cvt_f32_ubyte2_e32 v210, v176
	v_cvt_f32_ubyte3_e32 v176, v176
	v_max_f32_e32 v213, 0.5, v176
	v_cvt_f32_ubyte0_e32 v176, v177
	v_max_f32_e32 v212, 0.5, v210
	v_max_f32_e32 v210, 0.5, v176
	v_cvt_f32_ubyte1_e32 v176, v177
	v_max_f32_e32 v214, 0.5, v176
	v_cvt_f32_ubyte2_e32 v176, v177
	v_max_f32_e32 v1, 0.5, v1
	v_max_f32_e32 v215, 0.5, v176
	v_cvt_f32_ubyte3_e32 v176, v177
	v_max_f32_e32 v216, 0.5, v176
	v_rcp_f32_e32 v176, v1
	v_rcp_f32_e32 v177, v211
	v_rcp_f32_e32 v210, v210
	v_rcp_f32_e32 v211, v214
	v_rcp_f32_e32 v212, v212
	v_rcp_f32_e32 v213, v213
	v_rcp_f32_e32 v214, v215
	v_rcp_f32_e32 v215, v216
	v_pk_mul_f32 v[172:173], v[172:173], v[176:177]
	v_cvt_f32_ubyte0_e32 v1, v184
	v_pk_mul_f32 v[56:57], v[56:57], v[172:173]
	v_pk_mul_f32 v[172:173], v[208:209], v[210:211]
	v_pk_mul_f32 v[174:175], v[174:175], v[212:213]
	v_pk_mul_f32 v[52:53], v[52:53], v[172:173]
	v_max_f32_e32 v172, 0.5, v1
	v_cvt_f32_ubyte1_e32 v1, v184
	v_pk_mul_f32 v[58:59], v[58:59], v[174:175]
	v_pk_mul_f32 v[174:175], v[178:179], v[214:215]
	v_max_f32_e32 v173, 0.5, v1
	v_cvt_f32_ubyte2_e32 v1, v184
	v_pk_mul_f32 v[54:55], v[54:55], v[174:175]
	v_max_f32_e32 v174, 0.5, v1
	v_cvt_f32_ubyte3_e32 v1, v184
	v_max_f32_e32 v175, 0.5, v1
	v_cvt_f32_ubyte0_e32 v1, v185
	v_max_f32_e32 v176, 0.5, v1
	v_cvt_f32_ubyte1_e32 v1, v185
	v_max_f32_e32 v177, 0.5, v1
	v_cvt_f32_ubyte2_e32 v1, v185
	v_cvt_f32_ubyte1_e32 v184, v186
	v_max_f32_e32 v178, 0.5, v1
	v_cvt_f32_ubyte3_e32 v1, v185
	v_max_f32_e32 v185, 0.5, v184
	v_cvt_f32_ubyte2_e32 v184, v186
	v_max_f32_e32 v208, 0.5, v184
	v_cvt_f32_ubyte3_e32 v184, v186
	v_max_f32_e32 v209, 0.5, v184
	v_cvt_f32_ubyte0_e32 v184, v187
	v_max_f32_e32 v179, 0.5, v1
	v_cvt_f32_ubyte0_e32 v1, v186
	v_max_f32_e32 v186, 0.5, v184
	v_cvt_f32_ubyte1_e32 v184, v187
	v_max_f32_e32 v210, 0.5, v184
	v_cvt_f32_ubyte2_e32 v184, v187
	v_max_f32_e32 v1, 0.5, v1
	v_max_f32_e32 v211, 0.5, v184
	v_cvt_f32_ubyte3_e32 v184, v187
	v_max_f32_e32 v212, 0.5, v184
	v_rcp_f32_e32 v184, v1
	v_rcp_f32_e32 v185, v185
	v_rcp_f32_e32 v186, v186
	v_rcp_f32_e32 v187, v210
	v_rcp_f32_e32 v208, v208
	v_rcp_f32_e32 v209, v209
	v_rcp_f32_e32 v210, v211
	v_rcp_f32_e32 v211, v212
	v_pk_mul_f32 v[172:173], v[172:173], v[184:185]
	v_cvt_f32_ubyte0_e32 v1, v170
	v_pk_mul_f32 v[48:49], v[48:49], v[172:173]
	v_pk_mul_f32 v[172:173], v[176:177], v[186:187]
	v_pk_mul_f32 v[174:175], v[174:175], v[208:209]
	v_pk_mul_f32 v[44:45], v[44:45], v[172:173]
	v_max_f32_e32 v172, 0.5, v1
	v_cvt_f32_ubyte1_e32 v1, v170
	v_pk_mul_f32 v[50:51], v[50:51], v[174:175]
	v_pk_mul_f32 v[174:175], v[178:179], v[210:211]
	v_max_f32_e32 v173, 0.5, v1
	v_cvt_f32_ubyte2_e32 v1, v170
	v_pk_mul_f32 v[46:47], v[46:47], v[174:175]
	v_max_f32_e32 v174, 0.5, v1
	v_cvt_f32_ubyte3_e32 v1, v170
	v_max_f32_e32 v175, 0.5, v1
	v_cvt_f32_ubyte0_e32 v1, v171
	v_max_f32_e32 v176, 0.5, v1
	v_cvt_f32_ubyte1_e32 v1, v171
	v_max_f32_e32 v177, 0.5, v1
	v_cvt_f32_ubyte2_e32 v1, v171
	v_max_f32_e32 v170, 0.5, v1
	v_cvt_f32_ubyte3_e32 v1, v171
	v_cvt_f32_ubyte1_e32 v178, v168
	v_max_f32_e32 v171, 0.5, v1
	v_cvt_f32_ubyte0_e32 v1, v168
	v_max_f32_e32 v179, 0.5, v178
	v_cvt_f32_ubyte2_e32 v178, v168
	v_cvt_f32_ubyte3_e32 v168, v168
	v_max_f32_e32 v185, 0.5, v168
	v_cvt_f32_ubyte0_e32 v168, v169
	v_max_f32_e32 v184, 0.5, v178
	v_max_f32_e32 v178, 0.5, v168
	v_cvt_f32_ubyte1_e32 v168, v169
	v_max_f32_e32 v186, 0.5, v168
	v_cvt_f32_ubyte2_e32 v168, v169
	v_max_f32_e32 v1, 0.5, v1
	v_max_f32_e32 v187, 0.5, v168
; __device__ __forceinline__ f32x4 un_unorm8(unsigned w) { return (f32x4){fmaxf((float)(w & 255u), 0.5f), fmaxf((float)((w >> 8) & 255u), 0.5f), fmaxf((float)((w >> 16) & 255u), 0.5f), fmaxf((float)(w >> 24), 0.5f)}; }
;     __device__ __forceinline__ void seam(f32x4 (&acc)[2][2][4][2], const Unit& u, int n, int wr, int wc, int fr, int fq) const {
;     ...
;             for (int m = 0; m < 4; ++m)
; #pragma unroll
;                 for (int bj = 0; bj < 2; ++bj) { const f32x4 a0 = un_unorm8(ga[m][bj].x), a1 = un_unorm8(ga[m][bj].y), b0 = un_unorm8(gb[m][bj].x), b1 = un_unorm8(gb[m][bj].y);
; #pragma unroll
;                     for (int j = 0; j < 4; ++j) { acc[ai][bj][m][0][j] *= a0[j] * __builtin_amdgcn_rcpf(b0[j]); acc[ai][bj][m][1][j] *= a1[j] * __builtin_amdgcn_rcpf(b1[j]); } }
;             asm volatile("" ::: "memory");
;         }
	v_cvt_f32_ubyte3_e32 v168, v169
	v_max_f32_e32 v208, 0.5, v168
	v_rcp_f32_e32 v168, v1
	v_rcp_f32_e32 v169, v179
	v_rcp_f32_e32 v178, v178
	v_rcp_f32_e32 v179, v186
	v_rcp_f32_e32 v186, v187
	v_rcp_f32_e32 v187, v208
	v_pk_mul_f32 v[168:169], v[172:173], v[168:169]
	v_rcp_f32_e32 v184, v184
	v_rcp_f32_e32 v185, v185
	v_pk_mul_f32 v[40:41], v[40:41], v[168:169]
	v_pk_mul_f32 v[168:169], v[176:177], v[178:179]
	v_cvt_f32_ubyte0_e32 v1, v160
	v_pk_mul_f32 v[36:37], v[36:37], v[168:169]
	v_max_f32_e32 v168, 0.5, v1
	v_cvt_f32_ubyte1_e32 v1, v160
	v_pk_mul_f32 v[170:171], v[170:171], v[186:187]
	v_max_f32_e32 v169, 0.5, v1
	v_cvt_f32_ubyte2_e32 v1, v160
	v_pk_mul_f32 v[38:39], v[38:39], v[170:171]
	v_max_f32_e32 v170, 0.5, v1
	v_cvt_f32_ubyte3_e32 v1, v160
	v_pk_mul_f32 v[172:173], v[174:175], v[184:185]
	v_max_f32_e32 v171, 0.5, v1
	v_cvt_f32_ubyte0_e32 v1, v161
	v_pk_mul_f32 v[42:43], v[42:43], v[172:173]
	v_max_f32_e32 v172, 0.5, v1
	v_cvt_f32_ubyte1_e32 v1, v161
	v_max_f32_e32 v173, 0.5, v1
	v_cvt_f32_ubyte2_e32 v1, v161
	v_max_f32_e32 v160, 0.5, v1
	v_cvt_f32_ubyte3_e32 v1, v161
	v_cvt_f32_ubyte1_e32 v174, v158
	v_max_f32_e32 v161, 0.5, v1
	v_cvt_f32_ubyte0_e32 v1, v158
	v_max_f32_e32 v175, 0.5, v174
	v_cvt_f32_ubyte2_e32 v174, v158
	v_cvt_f32_ubyte3_e32 v158, v158
	v_max_f32_e32 v177, 0.5, v158
	v_cvt_f32_ubyte0_e32 v158, v159
	v_max_f32_e32 v176, 0.5, v174
	v_max_f32_e32 v174, 0.5, v158
	v_cvt_f32_ubyte1_e32 v158, v159
	v_max_f32_e32 v178, 0.5, v158
	v_cvt_f32_ubyte2_e32 v158, v159
	v_max_f32_e32 v1, 0.5, v1
	v_max_f32_e32 v179, 0.5, v158
	v_cvt_f32_ubyte3_e32 v158, v159
	v_max_f32_e32 v184, 0.5, v158
	v_rcp_f32_e32 v158, v1
	v_rcp_f32_e32 v159, v175
	v_rcp_f32_e32 v174, v174
	v_rcp_f32_e32 v175, v178
	v_rcp_f32_e32 v178, v179
	v_rcp_f32_e32 v179, v184
	v_pk_mul_f32 v[158:159], v[168:169], v[158:159]
	v_rcp_f32_e32 v176, v176
	v_rcp_f32_e32 v177, v177
	v_pk_mul_f32 v[32:33], v[32:33], v[158:159]
	v_pk_mul_f32 v[158:159], v[172:173], v[174:175]
	v_cvt_f32_ubyte0_e32 v1, v156
	v_pk_mul_f32 v[28:29], v[28:29], v[158:159]
	v_max_f32_e32 v158, 0.5, v1
	v_cvt_f32_ubyte1_e32 v1, v156
	v_pk_mul_f32 v[160:161], v[160:161], v[178:179]
	v_max_f32_e32 v159, 0.5, v1
	v_cvt_f32_ubyte2_e32 v1, v156
	v_pk_mul_f32 v[30:31], v[30:31], v[160:161]
	v_max_f32_e32 v160, 0.5, v1
	v_cvt_f32_ubyte3_e32 v1, v156
	v_pk_mul_f32 v[168:169], v[170:171], v[176:177]
	v_max_f32_e32 v161, 0.5, v1
	v_cvt_f32_ubyte0_e32 v1, v157
	v_pk_mul_f32 v[34:35], v[34:35], v[168:169]
	v_max_f32_e32 v168, 0.5, v1
	v_cvt_f32_ubyte1_e32 v1, v157
	v_max_f32_e32 v169, 0.5, v1
	v_cvt_f32_ubyte2_e32 v1, v157
	v_max_f32_e32 v156, 0.5, v1
	v_cvt_f32_ubyte3_e32 v1, v157
	v_cvt_f32_ubyte1_e32 v170, v154
	v_max_f32_e32 v157, 0.5, v1
	v_cvt_f32_ubyte0_e32 v1, v154
	v_max_f32_e32 v171, 0.5, v170
	v_cvt_f32_ubyte2_e32 v170, v154
	v_cvt_f32_ubyte3_e32 v154, v154
	v_max_f32_e32 v173, 0.5, v154
	v_cvt_f32_ubyte0_e32 v154, v155
	v_max_f32_e32 v172, 0.5, v170
	v_max_f32_e32 v170, 0.5, v154
	v_cvt_f32_ubyte1_e32 v154, v155
	v_max_f32_e32 v174, 0.5, v154
	v_cvt_f32_ubyte2_e32 v154, v155
	v_max_f32_e32 v1, 0.5, v1
	v_max_f32_e32 v175, 0.5, v154
	v_cvt_f32_ubyte3_e32 v154, v155
	v_max_f32_e32 v176, 0.5, v154
	v_rcp_f32_e32 v154, v1
	v_rcp_f32_e32 v155, v171
	v_rcp_f32_e32 v170, v170
	v_rcp_f32_e32 v171, v174
	v_rcp_f32_e32 v174, v175
	v_rcp_f32_e32 v175, v176
	v_pk_mul_f32 v[154:155], v[158:159], v[154:155]
	v_rcp_f32_e32 v172, v172
	v_rcp_f32_e32 v173, v173
	v_pk_mul_f32 v[24:25], v[24:25], v[154:155]
	v_pk_mul_f32 v[154:155], v[168:169], v[170:171]
	s_waitcnt vmcnt(0)
	v_cvt_f32_ubyte0_e32 v1, v152
	v_pk_mul_f32 v[20:21], v[20:21], v[154:155]
	v_max_f32_e32 v154, 0.5, v1
	v_cvt_f32_ubyte1_e32 v1, v152
	v_pk_mul_f32 v[156:157], v[156:157], v[174:175]
	v_max_f32_e32 v155, 0.5, v1
	v_cvt_f32_ubyte2_e32 v1, v152
	v_pk_mul_f32 v[22:23], v[22:23], v[156:157]
	v_max_f32_e32 v156, 0.5, v1
	v_cvt_f32_ubyte3_e32 v1, v152
	v_pk_mul_f32 v[158:159], v[160:161], v[172:173]
	v_max_f32_e32 v157, 0.5, v1
	v_cvt_f32_ubyte0_e32 v1, v153
	v_pk_mul_f32 v[26:27], v[26:27], v[158:159]
	v_max_f32_e32 v158, 0.5, v1
	v_cvt_f32_ubyte1_e32 v1, v153
	v_max_f32_e32 v159, 0.5, v1
	v_cvt_f32_ubyte2_e32 v1, v153
	v_max_f32_e32 v152, 0.5, v1
	v_cvt_f32_ubyte3_e32 v1, v153
	v_cvt_f32_ubyte1_e32 v160, v150
	v_max_f32_e32 v153, 0.5, v1
	v_cvt_f32_ubyte0_e32 v1, v150
	v_max_f32_e32 v161, 0.5, v160
	v_cvt_f32_ubyte2_e32 v160, v150
	v_cvt_f32_ubyte3_e32 v150, v150
	v_max_f32_e32 v169, 0.5, v150
	v_cvt_f32_ubyte0_e32 v150, v151
	v_max_f32_e32 v168, 0.5, v160
	v_max_f32_e32 v160, 0.5, v150
	v_cvt_f32_ubyte1_e32 v150, v151
	v_max_f32_e32 v170, 0.5, v150
	v_cvt_f32_ubyte2_e32 v150, v151
	v_max_f32_e32 v1, 0.5, v1
	v_max_f32_e32 v171, 0.5, v150
	v_cvt_f32_ubyte3_e32 v150, v151
	v_max_f32_e32 v172, 0.5, v150
	v_rcp_f32_e32 v150, v1
	v_rcp_f32_e32 v151, v161
	v_rcp_f32_e32 v160, v160
	v_rcp_f32_e32 v161, v170
	v_rcp_f32_e32 v170, v171
	v_rcp_f32_e32 v171, v172
	v_pk_mul_f32 v[150:151], v[154:155], v[150:151]
	v_rcp_f32_e32 v168, v168
	v_rcp_f32_e32 v169, v169
	v_pk_mul_f32 v[16:17], v[16:17], v[150:151]
	v_pk_mul_f32 v[150:151], v[158:159], v[160:161]
	v_cvt_f32_ubyte0_e32 v1, v148
	v_pk_mul_f32 v[12:13], v[12:13], v[150:151]
	v_max_f32_e32 v150, 0.5, v1
	v_cvt_f32_ubyte1_e32 v1, v148
	v_pk_mul_f32 v[152:153], v[152:153], v[170:171]
	v_max_f32_e32 v151, 0.5, v1
	v_cvt_f32_ubyte2_e32 v1, v148
	v_pk_mul_f32 v[14:15], v[14:15], v[152:153]
	v_max_f32_e32 v152, 0.5, v1
	v_cvt_f32_ubyte3_e32 v1, v148
	v_pk_mul_f32 v[154:155], v[156:157], v[168:169]
	v_max_f32_e32 v153, 0.5, v1
	v_cvt_f32_ubyte0_e32 v1, v149
	v_pk_mul_f32 v[18:19], v[18:19], v[154:155]
	v_max_f32_e32 v154, 0.5, v1
	v_cvt_f32_ubyte1_e32 v1, v149
	v_max_f32_e32 v155, 0.5, v1
	v_cvt_f32_ubyte2_e32 v1, v149
	v_max_f32_e32 v148, 0.5, v1
	v_cvt_f32_ubyte3_e32 v1, v149
	v_cvt_f32_ubyte1_e32 v156, v2
	v_max_f32_e32 v149, 0.5, v1
	v_cvt_f32_ubyte0_e32 v1, v2
	v_max_f32_e32 v157, 0.5, v156
	v_cvt_f32_ubyte2_e32 v156, v2
	v_cvt_f32_ubyte3_e32 v2, v2
	v_max_f32_e32 v159, 0.5, v2
	v_cvt_f32_ubyte0_e32 v2, v3
	v_max_f32_e32 v158, 0.5, v156
	v_max_f32_e32 v156, 0.5, v2
	v_cvt_f32_ubyte1_e32 v2, v3
	v_max_f32_e32 v160, 0.5, v2
	v_cvt_f32_ubyte2_e32 v2, v3
	v_max_f32_e32 v1, 0.5, v1
	v_max_f32_e32 v161, 0.5, v2
	v_cvt_f32_ubyte3_e32 v2, v3
	v_max_f32_e32 v168, 0.5, v2
	v_rcp_f32_e32 v2, v1
	v_rcp_f32_e32 v3, v157
	v_rcp_f32_e32 v156, v156
	v_rcp_f32_e32 v158, v158
	v_rcp_f32_e32 v159, v159
	v_rcp_f32_e32 v157, v160
	v_rcp_f32_e32 v160, v161
	v_rcp_f32_e32 v161, v168
	v_pk_mul_f32 v[2:3], v[150:151], v[2:3]
	v_pk_mul_f32 v[150:151], v[152:153], v[158:159]
	v_pk_mul_f32 v[8:9], v[8:9], v[2:3]
	v_pk_mul_f32 v[2:3], v[154:155], v[156:157]
	v_pk_mul_f32 v[148:149], v[148:149], v[160:161]
	v_pk_mul_f32 v[10:11], v[10:11], v[150:151]
	v_pk_mul_f32 v[6:7], v[6:7], v[148:149]
	v_pk_mul_f32 v[4:5], v[4:5], v[2:3]
	s_andn2_b64 vcc, exec, s[44:45]
	s_cbranch_vccnz .Lsm_b
	s_barrier
